# FFN-up column scales staged in LDS once per phase (x 1/127); SwiGLU epilogue reads them with ds_read_b128, so it no longer waits on vmcnt (no drain of the next tile's prefetched LDS-DMA)
# baseline (speedup 1.0000x reference)
; #define PG8_STAGE(bufoff, gbase, voff) do { _Pragma("unroll") for (int _i = 0; _i < 2; ++_i) \
;         __builtin_amdgcn_global_load_lds((const unsigned*)((const char*)(gbase) + (voff)[_i]), (PG8_LAS unsigned*)(lds + (bufoff) + ldsw + _i * 8192), 16, 0, 0); } while (0)
; #define PG8_WAIT_V(n) asm volatile("s_waitcnt vmcnt(" #n ")" ::: "memory")
; #define PG8_BAR __builtin_amdgcn_s_barrier()
;     ...
;     if constexpr (SP2) {
;         PG8_STAGE(PG8_SB(0, 0), cB, voffB); PG8_STAGE(PG8_SB(0, 1), cB + hstepB, voffB); PG8_STAGE(PG8_SA(0, 0), cA, voffA); PG8_STAGE(PG8_SA(0, 1), cA + hstep, voffA);
;         if (wr == 1) PG8_BAR;
;         PG8_WAIT_V(2); PG8_BAR;
;         PG8_STAGE(PG8_SB(1, 0), cB + kstepB, voffB); PG8_STAGE(PG8_SA(1, 0), cA + kstep, voffA); PG8_STAGE(PG8_SB(1, 1), cB + hstepB + kstepB, voffB);
;         PG8_WAIT_V(6); PG8_BAR;
;     __device__ __forceinline__ void operator()(const i32x4 (&acc)[2][2][4][2], const pg8::Unit& u, int wr, int wc, int fr_, int fq_, int tid) {
;     ...
;         const float* cp = cmax + u.pn * 256 + wc * 32 + 8 * fq;
;         f32x4 cs[2][2];
;         cs[0][0] = *(const f32x4*)(cp) * (1.0f / 127.0f); cs[0][1] = *(const f32x4*)(cp + 4) * (1.0f / 127.0f);
;         cs[1][0] = *(const f32x4*)(cp + 128) * (1.0f / 127.0f); cs[1][1] = *(const f32x4*)(cp + 132) * (1.0f / 127.0f);
.LBB0_157:
	s_add_u32 s8, s10, 0x2d800000
	s_addc_u32 s9, s11, 0
	s_mul_hi_i32 s15, s14, 0xb000
	s_mul_i32 s14, s14, 0xb000
	s_add_u32 s14, s10, s14
	s_addc_u32 s15, s11, s15
	s_lshl_b32 s10, s13, 5
	s_and_b32 s41, s10, 0x60
	s_lshl_b32 s40, s5, 6
	s_lshl_b32 s16, s5, 13
	s_lshl_b32 s13, s41, 7
	s_add_u32 s10, s22, 0x8000
	v_mov_b32_e32 v135, v163
	s_addc_u32 s11, s23, 0
	v_mov_b32_e32 v131, v163
	s_add_i32 m0, s36, 0x18000
	v_lshl_add_u64 v[12:13], s[10:11], 0, v[134:135]
	s_waitcnt vmcnt(2)
	s_barrier
	global_load_lds_dwordx4 v[12:13], off
	v_lshl_add_u64 v[12:13], s[10:11], 0, v[130:131]
	s_add_i32 m0, s36, 0x1a000
	s_add_i32 s42, s36, 0x8000
	s_add_i32 s43, s36, 0xa000
	global_load_lds_dwordx4 v[12:13], off
	v_lshl_add_u64 v[2:3], v[2:3], 0, s[78:79]
	s_mov_b32 m0, s42
	s_add_u32 s10, s22, 0xc000
	global_load_lds_dwordx4 v[2:3], off
	v_lshl_add_u64 v[2:3], v[4:5], 0, s[78:79]
	s_mov_b32 m0, s43
	s_addc_u32 s11, s23, 0
	global_load_lds_dwordx4 v[2:3], off
	s_add_i32 m0, s36, 0x1c000
	v_lshl_add_u64 v[2:3], s[10:11], 0, v[134:135]
	global_load_lds_dwordx4 v[2:3], off
	v_lshl_add_u64 v[2:3], s[10:11], 0, v[130:131]
	s_add_i32 m0, s36, 0x1e000
	v_bfe_u32 v155, v72, 4, 2
	global_load_lds_dwordx4 v[2:3], off
	v_and_b32_e32 v1, 15, v72
	v_lshlrev_b32_e32 v2, 4, v155
	v_lshlrev_b32_e32 v3, 2, v72
	v_lshl_or_b32 v2, v1, 6, v2
	v_and_b32_e32 v3, 32, v3
	v_bitop3_b32 v4, v2, s16, v3 bitop3:0xde
	v_bitop3_b32 v158, s13, v2, v3 bitop3:0xf6
	v_lshlrev_b32_e32 v2, 14, v10
	s_cmpk_lt_u32 s12, 0x100
	v_and_b32_e32 v2, 0xffff8000, v2
	s_sext_i32_i16 s21, s4
	s_cselect_b64 s[10:11], -1, 0
	s_ashr_i32 s44, s29, 31
	s_lshl_b32 s4, s41, 2
	v_lshl_add_u32 v2, v9, 11, v2
	v_and_b32_e32 v3, 1, v10
	s_add_u32 s4, s14, s4
	v_lshl_or_b32 v2, v3, 6, v2
	s_addc_u32 s12, s15, 0
	v_lshl_add_u32 v138, v11, 1, v2
	v_lshlrev_b32_e32 v2, 14, v6
	s_add_u32 s45, s4, 0x80000
	v_and_b32_e32 v2, 0xffff8000, v2
	s_waitcnt vmcnt(6)
	s_addc_u32 s46, s12, 0
	s_lshl_b32 s4, s5, 8
	v_lshl_add_u32 v2, v7, 11, v2
	v_and_b32_e32 v3, 1, v6
	s_add_i32 s47, s4, 0
	v_lshl_or_b32 v2, v3, 6, v2
	s_add_i32 s47, s47, 0x20400
	v_mov_b32_e32 v139, v163
	v_lshl_add_u32 v140, v8, 1, v2
	v_mov_b32_e32 v141, v163
	s_mov_b32 s48, 0
	v_add_u32_e32 v159, 0, v4
	v_and_b32_e32 v216, 31, v195
	v_lshrrev_b32_e32 v217, 5, v195
	v_lshl_add_u32 v216, v217, 7, v216
	v_lshlrev_b32_e32 v216, 2, v216
	s_lshl_b32 s96, s21, 10
	s_add_u32 s100, s45, s96
	s_addc_u32 s101, s46, 0
	global_load_dword v220, v216, s[100:101]
	s_add_u32 s100, s100, 0x1000
	s_addc_u32 s101, s101, 0
	global_load_dword v221, v216, s[100:101]
	s_add_u32 s100, s100, 0x1000
	s_addc_u32 s101, s101, 0
	global_load_dword v222, v216, s[100:101]
	s_add_u32 s100, s100, 0x1000
	s_addc_u32 s101, s101, 0
	global_load_dword v223, v216, s[100:101]
	s_add_u32 s100, s100, 0x1000
	s_addc_u32 s101, s101, 0
	global_load_dword v224, v216, s[100:101]
	s_add_u32 s100, s100, 0x1000
	s_addc_u32 s101, s101, 0
	global_load_dword v225, v216, s[100:101]
	s_add_u32 s100, s100, 0x1000
	s_addc_u32 s101, s101, 0
	global_load_dword v226, v216, s[100:101]
	s_add_u32 s100, s100, 0x1000
	s_addc_u32 s101, s101, 0
	global_load_dword v227, v216, s[100:101]
	s_add_u32 s100, s100, 0x1000
	s_addc_u32 s101, s101, 0
	global_load_dword v228, v216, s[100:101]
	s_add_u32 s100, s100, 0x1000
	s_addc_u32 s101, s101, 0
	global_load_dword v229, v216, s[100:101]
	s_add_u32 s100, s100, 0x1000
	s_addc_u32 s101, s101, 0
	global_load_dword v230, v216, s[100:101]
	s_lshl_b32 s96, s41, 3
	s_add_i32 s96, s96, 0x21000
	v_lshl_add_u32 v217, v195, 2, s96
	s_waitcnt vmcnt(0)
	v_mul_f32_e32 v220, s76, v220
	v_mul_f32_e32 v221, s76, v221
	v_mul_f32_e32 v222, s76, v222
	v_mul_f32_e32 v223, s76, v223
	v_mul_f32_e32 v224, s76, v224
	v_mul_f32_e32 v225, s76, v225
	v_mul_f32_e32 v226, s76, v226
	v_mul_f32_e32 v227, s76, v227
	v_mul_f32_e32 v228, s76, v228
	v_mul_f32_e32 v229, s76, v229
	v_mul_f32_e32 v230, s76, v230
	ds_write_b32 v217, v220
	ds_write_b32 v217, v221 offset:1024
	ds_write_b32 v217, v222 offset:2048
	ds_write_b32 v217, v223 offset:3072
	ds_write_b32 v217, v224 offset:4096
	ds_write_b32 v217, v225 offset:5120
	ds_write_b32 v217, v226 offset:6144
	ds_write_b32 v217, v227 offset:7168
	ds_write_b32 v217, v228 offset:8192
	ds_write_b32 v217, v229 offset:9216
	ds_write_b32 v217, v230 offset:10240
	s_waitcnt lgkmcnt(0)
	s_barrier
	s_branch .LBB0_160

; __device__ __forceinline__ float silu_f(float x) { return x * __builtin_amdgcn_rcpf(1.0f + __builtin_amdgcn_exp2f(-1.4426950408889634f * x)); }
;     __device__ __forceinline__ void operator()(const i32x4 (&acc)[2][2][4][2], const pg8::Unit& u, int wr, int wc, int fr_, int fq_, int tid) {
;     ...
;         const int row0 = u.pm * 256 + wr * 64 + fr, col0 = u.pn * 128 + wc * 32 + 8 * fq;
;         const float* cp = cmax + u.pn * 256 + wc * 32 + 8 * fq;
;         f32x4 cs[2][2];
;         cs[0][0] = *(const f32x4*)(cp) * (1.0f / 127.0f); cs[0][1] = *(const f32x4*)(cp + 4) * (1.0f / 127.0f);
;         cs[1][0] = *(const f32x4*)(cp + 128) * (1.0f / 127.0f); cs[1][1] = *(const f32x4*)(cp + 132) * (1.0f / 127.0f);
; #pragma unroll
;         for (int ai = 0; ai < 2; ++ai)
; #pragma unroll
;             for (int m = 0; m < 4; ++m) {
;                 const int row = row0 + ai * 128 + m * 16;
;                 const float rs = rsl[wr * 64 + fr + ai * 128 + m * 16];
;                 f32x4 h[2];
; #pragma unroll
;                 for (int n = 0; n < 2; ++n) {
; #pragma unroll
;                     for (int i = 0; i < 4; ++i) { const float g = (float)acc[ai][0][m][n][i] * (rs * cs[0][n][i]), up = (float)acc[ai][1][m][n][i] * (rs * cs[1][n][i]); h[n][i] = silu_f(g) * up; } }
.LBB0_166:
	s_mul_i32 s13, s20, 0x58
	v_lshrrev_b32_e32 v175, 4, v195
	v_and_b32_e32 v174, 15, v195
	s_lshr_b32 s22, s21, 2
	s_lshl_b32 s22, s22, 10
	s_lshl_b32 s23, s41, 3
	s_add_i32 s22, s22, s23
	s_add_i32 s22, s22, 0x21000
	v_lshlrev_b32_e32 v176, 4, v175
	v_lshl_add_u32 v175, v175, 5, s22
	ds_read_b128 v[216:219], v175
	ds_read_b128 v[220:223], v175 offset:16
	ds_read_b128 v[224:227], v175 offset:128
	ds_read_b128 v[228:231], v175 offset:144
	v_add_u32_e32 v177, s40, v174
	v_lshl_add_u32 v174, v174, 2, s47
	ds_read_b32 v232, v174
	ds_read_b32 v234, v174 offset:64
	ds_read_b32 v236, v174 offset:128
	ds_read_b32 v238, v174 offset:192
	ds_read_b32 v240, v174 offset:512
	ds_read_b32 v242, v174 offset:576
	ds_read_b32 v244, v174 offset:640
	ds_read_b32 v246, v174 offset:704
	v_lshl_add_u32 v176, v177, 7, v176
	s_lshl_b32 s22, s21, 1
	s_add_i32 s13, s13, s22
	s_lshr_b32 s22, s41, 6
	s_add_i32 s13, s13, s22
	s_and_b32 s22, s41, 32
	s_lshl_b32 s22, s22, 1
	v_add_u32_e32 v176, s22, v176
	s_lshl_b32 s13, s13, 15
	s_add_u32 s20, s8, s13
	s_addc_u32 s21, s9, 0
	v_cvt_f32_i32_e32 v126, v126
	v_cvt_f32_i32_e32 v127, v127
	v_cvt_f32_i32_e32 v128, v128
	v_cvt_f32_i32_e32 v129, v129
	v_cvt_f32_i32_e32 v122, v122
	v_cvt_f32_i32_e32 v123, v123
	v_cvt_f32_i32_e32 v124, v124
	v_cvt_f32_i32_e32 v125, v125
	v_cvt_f32_i32_e32 v118, v118
	v_cvt_f32_i32_e32 v119, v119
	v_cvt_f32_i32_e32 v120, v120
	v_cvt_f32_i32_e32 v121, v121
	v_cvt_f32_i32_e32 v114, v114
	v_cvt_f32_i32_e32 v115, v115
	v_cvt_f32_i32_e32 v116, v116
	v_cvt_f32_i32_e32 v117, v117
	v_cvt_f32_i32_e32 v110, v110
	v_cvt_f32_i32_e32 v111, v111
	v_cvt_f32_i32_e32 v112, v112
	v_cvt_f32_i32_e32 v113, v113
	v_cvt_f32_i32_e32 v106, v106
	v_cvt_f32_i32_e32 v107, v107
	v_cvt_f32_i32_e32 v108, v108
	v_cvt_f32_i32_e32 v109, v109
	v_cvt_f32_i32_e32 v102, v102
	v_cvt_f32_i32_e32 v103, v103
	v_cvt_f32_i32_e32 v104, v104
	v_cvt_f32_i32_e32 v105, v105
	v_cvt_f32_i32_e32 v98, v98
	v_cvt_f32_i32_e32 v99, v99
	v_cvt_f32_i32_e32 v100, v100
	v_cvt_f32_i32_e32 v101, v101
	s_waitcnt lgkmcnt(0)
	v_mul_f32_e32 v233, v232, v232
	v_mul_f32_e32 v235, v234, v234
	v_mul_f32_e32 v237, v236, v236
	v_mul_f32_e32 v239, v238, v238
	v_mul_f32_e32 v241, v240, v240
	v_mul_f32_e32 v243, v242, v242
	v_mul_f32_e32 v245, v244, v244
	v_mul_f32_e32 v247, v246, v246
	v_mul_f32_e32 v232, 0xbfb8aa3b, v232
	v_mul_f32_e32 v234, 0xbfb8aa3b, v234
	v_mul_f32_e32 v236, 0xbfb8aa3b, v236
	v_mul_f32_e32 v238, 0xbfb8aa3b, v238
	v_mul_f32_e32 v240, 0xbfb8aa3b, v240
	v_mul_f32_e32 v242, 0xbfb8aa3b, v242
	v_mul_f32_e32 v244, 0xbfb8aa3b, v244
	v_mul_f32_e32 v246, 0xbfb8aa3b, v246
	v_cvt_f32_i32_e32 v94, v94
	v_cvt_f32_i32_e32 v95, v95
	v_cvt_f32_i32_e32 v96, v96
	v_cvt_f32_i32_e32 v97, v97
	v_cvt_f32_i32_e32 v90, v90
	v_cvt_f32_i32_e32 v91, v91
	v_cvt_f32_i32_e32 v92, v92
	v_cvt_f32_i32_e32 v93, v93
	v_cvt_f32_i32_e32 v86, v86
	v_cvt_f32_i32_e32 v87, v87
	v_cvt_f32_i32_e32 v88, v88
	v_cvt_f32_i32_e32 v89, v89
	v_cvt_f32_i32_e32 v82, v82
	v_cvt_f32_i32_e32 v83, v83
	v_cvt_f32_i32_e32 v84, v84
	v_cvt_f32_i32_e32 v85, v85
	v_pk_mul_f32 v[126:127], v[126:127], v[216:217]
	v_pk_mul_f32 v[128:129], v[128:129], v[218:219]
	v_pk_mul_f32 v[122:123], v[122:123], v[224:225]
	v_pk_mul_f32 v[124:125], v[124:125], v[226:227]
	v_pk_mul_f32 v[248:249], v[126:127], v[232:233] op_sel_hi:[1,0]
	v_pk_mul_f32 v[250:251], v[128:129], v[232:233] op_sel_hi:[1,0]
	v_pk_mul_f32 v[126:127], v[126:127], v[122:123]
	v_exp_f32_e32 v248, v248
	v_exp_f32_e32 v249, v249
	v_exp_f32_e32 v250, v250
	v_exp_f32_e32 v251, v251
	v_pk_mul_f32 v[128:129], v[128:129], v[124:125]
	v_pk_add_f32 v[248:249], v[248:249], 1.0 op_sel_hi:[1,0]
	v_pk_add_f32 v[250:251], v[250:251], 1.0 op_sel_hi:[1,0]
	v_rcp_f32_e32 v248, v248
	v_rcp_f32_e32 v249, v249
	v_rcp_f32_e32 v250, v250
	v_rcp_f32_e32 v251, v251
	v_pk_mul_f32 v[248:249], v[248:249], v[232:233] op_sel:[0,1] op_sel_hi:[1,1]
	v_pk_mul_f32 v[250:251], v[250:251], v[232:233] op_sel:[0,1] op_sel_hi:[1,1]
	v_pk_mul_f32 v[126:127], v[126:127], v[248:249]
	v_pk_mul_f32 v[128:129], v[128:129], v[250:251]
	v_cvt_pk_bf16_f32 v122, v126, v127
	v_cvt_pk_bf16_f32 v123, v128, v129
	v_pk_mul_f32 v[118:119], v[118:119], v[220:221]
	v_pk_mul_f32 v[120:121], v[120:121], v[222:223]
	v_pk_mul_f32 v[114:115], v[114:115], v[228:229]
	v_pk_mul_f32 v[116:117], v[116:117], v[230:231]
	v_pk_mul_f32 v[248:249], v[118:119], v[232:233] op_sel_hi:[1,0]
	v_pk_mul_f32 v[250:251], v[120:121], v[232:233] op_sel_hi:[1,0]
	v_pk_mul_f32 v[118:119], v[118:119], v[114:115]
	v_exp_f32_e32 v248, v248
	v_exp_f32_e32 v249, v249
	v_exp_f32_e32 v250, v250
	v_exp_f32_e32 v251, v251
	v_pk_mul_f32 v[120:121], v[120:121], v[116:117]
	v_pk_add_f32 v[248:249], v[248:249], 1.0 op_sel_hi:[1,0]
	v_pk_add_f32 v[250:251], v[250:251], 1.0 op_sel_hi:[1,0]
	v_rcp_f32_e32 v248, v248
	v_rcp_f32_e32 v249, v249
	v_rcp_f32_e32 v250, v250
	v_rcp_f32_e32 v251, v251
	v_pk_mul_f32 v[248:249], v[248:249], v[232:233] op_sel:[0,1] op_sel_hi:[1,1]
	v_pk_mul_f32 v[250:251], v[250:251], v[232:233] op_sel:[0,1] op_sel_hi:[1,1]
	v_pk_mul_f32 v[118:119], v[118:119], v[248:249]
	v_pk_mul_f32 v[120:121], v[120:121], v[250:251]
	v_cvt_pk_bf16_f32 v124, v118, v119
	v_cvt_pk_bf16_f32 v125, v120, v121
	s_mov_b64 s[22:23], s[20:21]
	global_store_dwordx4 v176, v[122:125], s[22:23] sc1
	v_cvt_f32_i32_e32 v78, v78
	v_cvt_f32_i32_e32 v79, v79
	v_cvt_f32_i32_e32 v80, v80
	v_cvt_f32_i32_e32 v81, v81
	v_cvt_f32_i32_e32 v74, v74
	v_cvt_f32_i32_e32 v75, v75
	v_cvt_f32_i32_e32 v76, v76
	v_cvt_f32_i32_e32 v77, v77
	v_cvt_f32_i32_e32 v70, v70
	v_cvt_f32_i32_e32 v71, v71
	v_cvt_f32_i32_e32 v72, v72
	v_cvt_f32_i32_e32 v73, v73
	v_cvt_f32_i32_e32 v66, v66
; __device__ __forceinline__ float silu_f(float x) { return x * __builtin_amdgcn_rcpf(1.0f + __builtin_amdgcn_exp2f(-1.4426950408889634f * x)); }
;     __device__ __forceinline__ void operator()(const i32x4 (&acc)[2][2][4][2], const pg8::Unit& u, int wr, int wc, int fr_, int fq_, int tid) {
;     ...
;         for (int ai = 0; ai < 2; ++ai)
; #pragma unroll
;             for (int m = 0; m < 4; ++m) {
;                 const int row = row0 + ai * 128 + m * 16;
;                 const float rs = rsl[wr * 64 + fr + ai * 128 + m * 16];
;                 f32x4 h[2];
; #pragma unroll
;                 for (int n = 0; n < 2; ++n) {
; #pragma unroll
;                     for (int i = 0; i < 4; ++i) { const float g = (float)acc[ai][0][m][n][i] * (rs * cs[0][n][i]), up = (float)acc[ai][1][m][n][i] * (rs * cs[1][n][i]); h[n][i] = silu_f(g) * up; } }
;                 *(u32x4*)(H + ((size_t)(u.pm * (DFF / 64) + (col0 >> 6)) * 256 + (size_t)(row & 255)) * 64 + (col0 & 63)) = pack8bf(h[0], h[1]);
	v_cvt_f32_i32_e32 v67, v67
	v_cvt_f32_i32_e32 v68, v68
	v_cvt_f32_i32_e32 v69, v69
	v_pk_mul_f32 v[110:111], v[110:111], v[216:217]
	v_pk_mul_f32 v[112:113], v[112:113], v[218:219]
	v_pk_mul_f32 v[106:107], v[106:107], v[224:225]
	v_pk_mul_f32 v[108:109], v[108:109], v[226:227]
	v_pk_mul_f32 v[248:249], v[110:111], v[234:235] op_sel_hi:[1,0]
	v_pk_mul_f32 v[250:251], v[112:113], v[234:235] op_sel_hi:[1,0]
	v_pk_mul_f32 v[110:111], v[110:111], v[106:107]
	v_exp_f32_e32 v248, v248
	v_exp_f32_e32 v249, v249
	v_exp_f32_e32 v250, v250
	v_exp_f32_e32 v251, v251
	v_pk_mul_f32 v[112:113], v[112:113], v[108:109]
	v_pk_add_f32 v[248:249], v[248:249], 1.0 op_sel_hi:[1,0]
	v_pk_add_f32 v[250:251], v[250:251], 1.0 op_sel_hi:[1,0]
	v_rcp_f32_e32 v248, v248
	v_rcp_f32_e32 v249, v249
	v_rcp_f32_e32 v250, v250
	v_rcp_f32_e32 v251, v251
	v_pk_mul_f32 v[248:249], v[248:249], v[234:235] op_sel:[0,1] op_sel_hi:[1,1]
	v_pk_mul_f32 v[250:251], v[250:251], v[234:235] op_sel:[0,1] op_sel_hi:[1,1]
	v_pk_mul_f32 v[110:111], v[110:111], v[248:249]
	v_pk_mul_f32 v[112:113], v[112:113], v[250:251]
	v_cvt_pk_bf16_f32 v106, v110, v111
	v_cvt_pk_bf16_f32 v107, v112, v113
	v_pk_mul_f32 v[102:103], v[102:103], v[220:221]
	v_pk_mul_f32 v[104:105], v[104:105], v[222:223]
	v_pk_mul_f32 v[98:99], v[98:99], v[228:229]
	v_pk_mul_f32 v[100:101], v[100:101], v[230:231]
	v_pk_mul_f32 v[248:249], v[102:103], v[234:235] op_sel_hi:[1,0]
	v_pk_mul_f32 v[250:251], v[104:105], v[234:235] op_sel_hi:[1,0]
	v_pk_mul_f32 v[102:103], v[102:103], v[98:99]
	v_exp_f32_e32 v248, v248
	v_exp_f32_e32 v249, v249
	v_exp_f32_e32 v250, v250
	v_exp_f32_e32 v251, v251
	v_pk_mul_f32 v[104:105], v[104:105], v[100:101]
	v_pk_add_f32 v[248:249], v[248:249], 1.0 op_sel_hi:[1,0]
	v_pk_add_f32 v[250:251], v[250:251], 1.0 op_sel_hi:[1,0]
	v_rcp_f32_e32 v248, v248
	v_rcp_f32_e32 v249, v249
	v_rcp_f32_e32 v250, v250
	v_rcp_f32_e32 v251, v251
	v_pk_mul_f32 v[248:249], v[248:249], v[234:235] op_sel:[0,1] op_sel_hi:[1,1]
	v_pk_mul_f32 v[250:251], v[250:251], v[234:235] op_sel:[0,1] op_sel_hi:[1,1]
	v_pk_mul_f32 v[102:103], v[102:103], v[248:249]
	v_pk_mul_f32 v[104:105], v[104:105], v[250:251]
	v_cvt_pk_bf16_f32 v108, v102, v103
	v_cvt_pk_bf16_f32 v109, v104, v105
	global_store_dwordx4 v176, v[106:109], s[22:23] offset:2048 sc1
	v_cvt_f32_i32_e32 v62, v62
	v_cvt_f32_i32_e32 v63, v63
	v_cvt_f32_i32_e32 v64, v64
	v_cvt_f32_i32_e32 v65, v65
	v_cvt_f32_i32_e32 v58, v58
	v_cvt_f32_i32_e32 v59, v59
	v_cvt_f32_i32_e32 v60, v60
	v_cvt_f32_i32_e32 v61, v61
	v_cvt_f32_i32_e32 v54, v54
	v_cvt_f32_i32_e32 v55, v55
	v_cvt_f32_i32_e32 v56, v56
	v_cvt_f32_i32_e32 v57, v57
	v_cvt_f32_i32_e32 v50, v50
	v_cvt_f32_i32_e32 v51, v51
	v_cvt_f32_i32_e32 v52, v52
	v_cvt_f32_i32_e32 v53, v53
	v_pk_mul_f32 v[94:95], v[94:95], v[216:217]
	v_pk_mul_f32 v[96:97], v[96:97], v[218:219]
	v_pk_mul_f32 v[90:91], v[90:91], v[224:225]
	v_pk_mul_f32 v[92:93], v[92:93], v[226:227]
	v_pk_mul_f32 v[248:249], v[94:95], v[236:237] op_sel_hi:[1,0]
	v_pk_mul_f32 v[250:251], v[96:97], v[236:237] op_sel_hi:[1,0]
	v_pk_mul_f32 v[94:95], v[94:95], v[90:91]
	v_exp_f32_e32 v248, v248
	v_exp_f32_e32 v249, v249
	v_exp_f32_e32 v250, v250
	v_exp_f32_e32 v251, v251
	v_pk_mul_f32 v[96:97], v[96:97], v[92:93]
	v_pk_add_f32 v[248:249], v[248:249], 1.0 op_sel_hi:[1,0]
	v_pk_add_f32 v[250:251], v[250:251], 1.0 op_sel_hi:[1,0]
	v_rcp_f32_e32 v248, v248
	v_rcp_f32_e32 v249, v249
	v_rcp_f32_e32 v250, v250
	v_rcp_f32_e32 v251, v251
	v_pk_mul_f32 v[248:249], v[248:249], v[236:237] op_sel:[0,1] op_sel_hi:[1,1]
	v_pk_mul_f32 v[250:251], v[250:251], v[236:237] op_sel:[0,1] op_sel_hi:[1,1]
	v_pk_mul_f32 v[94:95], v[94:95], v[248:249]
	v_pk_mul_f32 v[96:97], v[96:97], v[250:251]
	v_cvt_pk_bf16_f32 v90, v94, v95
	v_cvt_pk_bf16_f32 v91, v96, v97
	v_pk_mul_f32 v[86:87], v[86:87], v[220:221]
	v_pk_mul_f32 v[88:89], v[88:89], v[222:223]
	v_pk_mul_f32 v[82:83], v[82:83], v[228:229]
	v_pk_mul_f32 v[84:85], v[84:85], v[230:231]
	v_pk_mul_f32 v[248:249], v[86:87], v[236:237] op_sel_hi:[1,0]
	v_pk_mul_f32 v[250:251], v[88:89], v[236:237] op_sel_hi:[1,0]
	v_pk_mul_f32 v[86:87], v[86:87], v[82:83]
	v_exp_f32_e32 v248, v248
	v_exp_f32_e32 v249, v249
	v_exp_f32_e32 v250, v250
	v_exp_f32_e32 v251, v251
	v_pk_mul_f32 v[88:89], v[88:89], v[84:85]
	v_pk_add_f32 v[248:249], v[248:249], 1.0 op_sel_hi:[1,0]
	v_pk_add_f32 v[250:251], v[250:251], 1.0 op_sel_hi:[1,0]
	v_rcp_f32_e32 v248, v248
	v_rcp_f32_e32 v249, v249
	v_rcp_f32_e32 v250, v250
	v_rcp_f32_e32 v251, v251
	v_pk_mul_f32 v[248:249], v[248:249], v[236:237] op_sel:[0,1] op_sel_hi:[1,1]
	v_pk_mul_f32 v[250:251], v[250:251], v[236:237] op_sel:[0,1] op_sel_hi:[1,1]
	v_pk_mul_f32 v[86:87], v[86:87], v[248:249]
	v_pk_mul_f32 v[88:89], v[88:89], v[250:251]
	v_cvt_pk_bf16_f32 v92, v86, v87
	v_cvt_pk_bf16_f32 v93, v88, v89
	s_add_u32 s22, s20, 0x1000
	s_addc_u32 s23, s21, 0
	global_store_dwordx4 v176, v[90:93], s[22:23] sc1
	v_cvt_f32_i32_e32 v46, v46
	v_cvt_f32_i32_e32 v47, v47
	v_cvt_f32_i32_e32 v48, v48
	v_cvt_f32_i32_e32 v49, v49
	v_cvt_f32_i32_e32 v42, v42
	v_cvt_f32_i32_e32 v43, v43
	v_cvt_f32_i32_e32 v44, v44
	v_cvt_f32_i32_e32 v45, v45
	v_cvt_f32_i32_e32 v38, v38
	v_cvt_f32_i32_e32 v39, v39
	v_cvt_f32_i32_e32 v40, v40
	v_cvt_f32_i32_e32 v41, v41
	v_cvt_f32_i32_e32 v34, v34
	v_cvt_f32_i32_e32 v35, v35
	v_cvt_f32_i32_e32 v36, v36
	v_cvt_f32_i32_e32 v37, v37
	v_pk_mul_f32 v[78:79], v[78:79], v[216:217]
	v_pk_mul_f32 v[80:81], v[80:81], v[218:219]
	v_pk_mul_f32 v[74:75], v[74:75], v[224:225]
	v_pk_mul_f32 v[76:77], v[76:77], v[226:227]
	v_pk_mul_f32 v[248:249], v[78:79], v[238:239] op_sel_hi:[1,0]
	v_pk_mul_f32 v[250:251], v[80:81], v[238:239] op_sel_hi:[1,0]
; __device__ __forceinline__ float silu_f(float x) { return x * __builtin_amdgcn_rcpf(1.0f + __builtin_amdgcn_exp2f(-1.4426950408889634f * x)); }
;     __device__ __forceinline__ void operator()(const i32x4 (&acc)[2][2][4][2], const pg8::Unit& u, int wr, int wc, int fr_, int fq_, int tid) {
;     ...
;         for (int ai = 0; ai < 2; ++ai)
; #pragma unroll
;             for (int m = 0; m < 4; ++m) {
;                 const int row = row0 + ai * 128 + m * 16;
;                 const float rs = rsl[wr * 64 + fr + ai * 128 + m * 16];
;                 f32x4 h[2];
; #pragma unroll
;                 for (int n = 0; n < 2; ++n) {
; #pragma unroll
;                     for (int i = 0; i < 4; ++i) { const float g = (float)acc[ai][0][m][n][i] * (rs * cs[0][n][i]), up = (float)acc[ai][1][m][n][i] * (rs * cs[1][n][i]); h[n][i] = silu_f(g) * up; } }
;                 *(u32x4*)(H + ((size_t)(u.pm * (DFF / 64) + (col0 >> 6)) * 256 + (size_t)(row & 255)) * 64 + (col0 & 63)) = pack8bf(h[0], h[1]);
	v_pk_mul_f32 v[78:79], v[78:79], v[74:75]
	v_exp_f32_e32 v248, v248
	v_exp_f32_e32 v249, v249
	v_exp_f32_e32 v250, v250
	v_exp_f32_e32 v251, v251
	v_pk_mul_f32 v[80:81], v[80:81], v[76:77]
	v_pk_add_f32 v[248:249], v[248:249], 1.0 op_sel_hi:[1,0]
	v_pk_add_f32 v[250:251], v[250:251], 1.0 op_sel_hi:[1,0]
	v_rcp_f32_e32 v248, v248
	v_rcp_f32_e32 v249, v249
	v_rcp_f32_e32 v250, v250
	v_rcp_f32_e32 v251, v251
	v_pk_mul_f32 v[248:249], v[248:249], v[238:239] op_sel:[0,1] op_sel_hi:[1,1]
	v_pk_mul_f32 v[250:251], v[250:251], v[238:239] op_sel:[0,1] op_sel_hi:[1,1]
	v_pk_mul_f32 v[78:79], v[78:79], v[248:249]
	v_pk_mul_f32 v[80:81], v[80:81], v[250:251]
	v_cvt_pk_bf16_f32 v74, v78, v79
	v_cvt_pk_bf16_f32 v75, v80, v81
	v_pk_mul_f32 v[70:71], v[70:71], v[220:221]
	v_pk_mul_f32 v[72:73], v[72:73], v[222:223]
	v_pk_mul_f32 v[66:67], v[66:67], v[228:229]
	v_pk_mul_f32 v[68:69], v[68:69], v[230:231]
	v_pk_mul_f32 v[248:249], v[70:71], v[238:239] op_sel_hi:[1,0]
	v_pk_mul_f32 v[250:251], v[72:73], v[238:239] op_sel_hi:[1,0]
	v_pk_mul_f32 v[70:71], v[70:71], v[66:67]
	v_exp_f32_e32 v248, v248
	v_exp_f32_e32 v249, v249
	v_exp_f32_e32 v250, v250
	v_exp_f32_e32 v251, v251
	v_pk_mul_f32 v[72:73], v[72:73], v[68:69]
	v_pk_add_f32 v[248:249], v[248:249], 1.0 op_sel_hi:[1,0]
	v_pk_add_f32 v[250:251], v[250:251], 1.0 op_sel_hi:[1,0]
	v_rcp_f32_e32 v248, v248
	v_rcp_f32_e32 v249, v249
	v_rcp_f32_e32 v250, v250
	v_rcp_f32_e32 v251, v251
	v_pk_mul_f32 v[248:249], v[248:249], v[238:239] op_sel:[0,1] op_sel_hi:[1,1]
	v_pk_mul_f32 v[250:251], v[250:251], v[238:239] op_sel:[0,1] op_sel_hi:[1,1]
	v_pk_mul_f32 v[70:71], v[70:71], v[248:249]
	v_pk_mul_f32 v[72:73], v[72:73], v[250:251]
	v_cvt_pk_bf16_f32 v76, v70, v71
	v_cvt_pk_bf16_f32 v77, v72, v73
	global_store_dwordx4 v176, v[74:77], s[22:23] offset:2048 sc1
	v_cvt_f32_i32_e32 v30, v30
	v_cvt_f32_i32_e32 v31, v31
	v_cvt_f32_i32_e32 v32, v32
	v_cvt_f32_i32_e32 v33, v33
	v_cvt_f32_i32_e32 v26, v26
	v_cvt_f32_i32_e32 v27, v27
	v_cvt_f32_i32_e32 v28, v28
	v_cvt_f32_i32_e32 v29, v29
	v_cvt_f32_i32_e32 v22, v22
	v_cvt_f32_i32_e32 v23, v23
	v_cvt_f32_i32_e32 v24, v24
	v_cvt_f32_i32_e32 v25, v25
	v_cvt_f32_i32_e32 v18, v18
	v_cvt_f32_i32_e32 v19, v19
	v_cvt_f32_i32_e32 v20, v20
	v_cvt_f32_i32_e32 v21, v21
	v_pk_mul_f32 v[62:63], v[62:63], v[216:217]
	v_pk_mul_f32 v[64:65], v[64:65], v[218:219]
	v_pk_mul_f32 v[58:59], v[58:59], v[224:225]
	v_pk_mul_f32 v[60:61], v[60:61], v[226:227]
	v_pk_mul_f32 v[248:249], v[62:63], v[240:241] op_sel_hi:[1,0]
	v_pk_mul_f32 v[250:251], v[64:65], v[240:241] op_sel_hi:[1,0]
	v_pk_mul_f32 v[62:63], v[62:63], v[58:59]
	v_exp_f32_e32 v248, v248
	v_exp_f32_e32 v249, v249
	v_exp_f32_e32 v250, v250
	v_exp_f32_e32 v251, v251
	v_pk_mul_f32 v[64:65], v[64:65], v[60:61]
	v_pk_add_f32 v[248:249], v[248:249], 1.0 op_sel_hi:[1,0]
	v_pk_add_f32 v[250:251], v[250:251], 1.0 op_sel_hi:[1,0]
	v_rcp_f32_e32 v248, v248
	v_rcp_f32_e32 v249, v249
	v_rcp_f32_e32 v250, v250
	v_rcp_f32_e32 v251, v251
	v_pk_mul_f32 v[248:249], v[248:249], v[240:241] op_sel:[0,1] op_sel_hi:[1,1]
	v_pk_mul_f32 v[250:251], v[250:251], v[240:241] op_sel:[0,1] op_sel_hi:[1,1]
	v_pk_mul_f32 v[62:63], v[62:63], v[248:249]
	v_pk_mul_f32 v[64:65], v[64:65], v[250:251]
	v_cvt_pk_bf16_f32 v58, v62, v63
	v_cvt_pk_bf16_f32 v59, v64, v65
	v_pk_mul_f32 v[54:55], v[54:55], v[220:221]
	v_pk_mul_f32 v[56:57], v[56:57], v[222:223]
	v_pk_mul_f32 v[50:51], v[50:51], v[228:229]
	v_pk_mul_f32 v[52:53], v[52:53], v[230:231]
	v_pk_mul_f32 v[248:249], v[54:55], v[240:241] op_sel_hi:[1,0]
	v_pk_mul_f32 v[250:251], v[56:57], v[240:241] op_sel_hi:[1,0]
	v_pk_mul_f32 v[54:55], v[54:55], v[50:51]
	v_exp_f32_e32 v248, v248
	v_exp_f32_e32 v249, v249
	v_exp_f32_e32 v250, v250
	v_exp_f32_e32 v251, v251
	v_pk_mul_f32 v[56:57], v[56:57], v[52:53]
	v_pk_add_f32 v[248:249], v[248:249], 1.0 op_sel_hi:[1,0]
	v_pk_add_f32 v[250:251], v[250:251], 1.0 op_sel_hi:[1,0]
	v_rcp_f32_e32 v248, v248
	v_rcp_f32_e32 v249, v249
	v_rcp_f32_e32 v250, v250
	v_rcp_f32_e32 v251, v251
	v_pk_mul_f32 v[248:249], v[248:249], v[240:241] op_sel:[0,1] op_sel_hi:[1,1]
	v_pk_mul_f32 v[250:251], v[250:251], v[240:241] op_sel:[0,1] op_sel_hi:[1,1]
	v_pk_mul_f32 v[54:55], v[54:55], v[248:249]
	v_pk_mul_f32 v[56:57], v[56:57], v[250:251]
	v_cvt_pk_bf16_f32 v60, v54, v55
	v_cvt_pk_bf16_f32 v61, v56, v57
	s_add_u32 s22, s20, 0x4000
	s_addc_u32 s23, s21, 0
	global_store_dwordx4 v176, v[58:61], s[22:23] sc1
	v_cvt_f32_i32_e32 v14, v14
	v_cvt_f32_i32_e32 v15, v15
	v_cvt_f32_i32_e32 v16, v16
	v_cvt_f32_i32_e32 v17, v17
	v_cvt_f32_i32_e32 v10, v10
	v_cvt_f32_i32_e32 v11, v11
	v_cvt_f32_i32_e32 v12, v12
	v_cvt_f32_i32_e32 v13, v13
	v_cvt_f32_i32_e32 v6, v6
	v_cvt_f32_i32_e32 v7, v7
	v_cvt_f32_i32_e32 v8, v8
	v_cvt_f32_i32_e32 v9, v9
	v_cvt_f32_i32_e32 v2, v2
	v_cvt_f32_i32_e32 v3, v3
	v_cvt_f32_i32_e32 v4, v4
	v_cvt_f32_i32_e32 v5, v5
	v_pk_mul_f32 v[46:47], v[46:47], v[216:217]
	v_pk_mul_f32 v[48:49], v[48:49], v[218:219]
	v_pk_mul_f32 v[42:43], v[42:43], v[224:225]
	v_pk_mul_f32 v[44:45], v[44:45], v[226:227]
	v_pk_mul_f32 v[248:249], v[46:47], v[242:243] op_sel_hi:[1,0]
	v_pk_mul_f32 v[250:251], v[48:49], v[242:243] op_sel_hi:[1,0]
	v_pk_mul_f32 v[46:47], v[46:47], v[42:43]
	v_exp_f32_e32 v248, v248
	v_exp_f32_e32 v249, v249
	v_exp_f32_e32 v250, v250
	v_exp_f32_e32 v251, v251
	v_pk_mul_f32 v[48:49], v[48:49], v[44:45]
	v_pk_add_f32 v[248:249], v[248:249], 1.0 op_sel_hi:[1,0]
	v_pk_add_f32 v[250:251], v[250:251], 1.0 op_sel_hi:[1,0]
	v_rcp_f32_e32 v248, v248
	v_rcp_f32_e32 v249, v249
	v_rcp_f32_e32 v250, v250
	v_rcp_f32_e32 v251, v251
	v_pk_mul_f32 v[248:249], v[248:249], v[242:243] op_sel:[0,1] op_sel_hi:[1,1]
; __device__ __forceinline__ float silu_f(float x) { return x * __builtin_amdgcn_rcpf(1.0f + __builtin_amdgcn_exp2f(-1.4426950408889634f * x)); }
;     __device__ __forceinline__ void operator()(const i32x4 (&acc)[2][2][4][2], const pg8::Unit& u, int wr, int wc, int fr_, int fq_, int tid) {
;     ...
;         for (int ai = 0; ai < 2; ++ai)
; #pragma unroll
;             for (int m = 0; m < 4; ++m) {
;                 const int row = row0 + ai * 128 + m * 16;
;                 const float rs = rsl[wr * 64 + fr + ai * 128 + m * 16];
;                 f32x4 h[2];
; #pragma unroll
;                 for (int n = 0; n < 2; ++n) {
; #pragma unroll
;                     for (int i = 0; i < 4; ++i) { const float g = (float)acc[ai][0][m][n][i] * (rs * cs[0][n][i]), up = (float)acc[ai][1][m][n][i] * (rs * cs[1][n][i]); h[n][i] = silu_f(g) * up; } }
;                 *(u32x4*)(H + ((size_t)(u.pm * (DFF / 64) + (col0 >> 6)) * 256 + (size_t)(row & 255)) * 64 + (col0 & 63)) = pack8bf(h[0], h[1]);
;             }
	v_pk_mul_f32 v[250:251], v[250:251], v[242:243] op_sel:[0,1] op_sel_hi:[1,1]
	v_pk_mul_f32 v[46:47], v[46:47], v[248:249]
	v_pk_mul_f32 v[48:49], v[48:49], v[250:251]
	v_cvt_pk_bf16_f32 v42, v46, v47
	v_cvt_pk_bf16_f32 v43, v48, v49
	v_pk_mul_f32 v[38:39], v[38:39], v[220:221]
	v_pk_mul_f32 v[40:41], v[40:41], v[222:223]
	v_pk_mul_f32 v[34:35], v[34:35], v[228:229]
	v_pk_mul_f32 v[36:37], v[36:37], v[230:231]
	v_pk_mul_f32 v[248:249], v[38:39], v[242:243] op_sel_hi:[1,0]
	v_pk_mul_f32 v[250:251], v[40:41], v[242:243] op_sel_hi:[1,0]
	v_pk_mul_f32 v[38:39], v[38:39], v[34:35]
	v_exp_f32_e32 v248, v248
	v_exp_f32_e32 v249, v249
	v_exp_f32_e32 v250, v250
	v_exp_f32_e32 v251, v251
	v_pk_mul_f32 v[40:41], v[40:41], v[36:37]
	v_pk_add_f32 v[248:249], v[248:249], 1.0 op_sel_hi:[1,0]
	v_pk_add_f32 v[250:251], v[250:251], 1.0 op_sel_hi:[1,0]
	v_rcp_f32_e32 v248, v248
	v_rcp_f32_e32 v249, v249
	v_rcp_f32_e32 v250, v250
	v_rcp_f32_e32 v251, v251
	v_pk_mul_f32 v[248:249], v[248:249], v[242:243] op_sel:[0,1] op_sel_hi:[1,1]
	v_pk_mul_f32 v[250:251], v[250:251], v[242:243] op_sel:[0,1] op_sel_hi:[1,1]
	v_pk_mul_f32 v[38:39], v[38:39], v[248:249]
	v_pk_mul_f32 v[40:41], v[40:41], v[250:251]
	v_cvt_pk_bf16_f32 v44, v38, v39
	v_cvt_pk_bf16_f32 v45, v40, v41
	global_store_dwordx4 v176, v[42:45], s[22:23] offset:2048 sc1
	v_pk_mul_f32 v[30:31], v[30:31], v[216:217]
	v_pk_mul_f32 v[32:33], v[32:33], v[218:219]
	v_pk_mul_f32 v[26:27], v[26:27], v[224:225]
	v_pk_mul_f32 v[28:29], v[28:29], v[226:227]
	v_pk_mul_f32 v[248:249], v[30:31], v[244:245] op_sel_hi:[1,0]
	v_pk_mul_f32 v[250:251], v[32:33], v[244:245] op_sel_hi:[1,0]
	v_pk_mul_f32 v[30:31], v[30:31], v[26:27]
	v_exp_f32_e32 v248, v248
	v_exp_f32_e32 v249, v249
	v_exp_f32_e32 v250, v250
	v_exp_f32_e32 v251, v251
	v_pk_mul_f32 v[32:33], v[32:33], v[28:29]
	v_pk_add_f32 v[248:249], v[248:249], 1.0 op_sel_hi:[1,0]
	v_pk_add_f32 v[250:251], v[250:251], 1.0 op_sel_hi:[1,0]
	v_rcp_f32_e32 v248, v248
	v_rcp_f32_e32 v249, v249
	v_rcp_f32_e32 v250, v250
	v_rcp_f32_e32 v251, v251
	v_pk_mul_f32 v[248:249], v[248:249], v[244:245] op_sel:[0,1] op_sel_hi:[1,1]
	v_pk_mul_f32 v[250:251], v[250:251], v[244:245] op_sel:[0,1] op_sel_hi:[1,1]
	v_pk_mul_f32 v[30:31], v[30:31], v[248:249]
	v_pk_mul_f32 v[32:33], v[32:33], v[250:251]
	v_cvt_pk_bf16_f32 v26, v30, v31
	v_cvt_pk_bf16_f32 v27, v32, v33
	v_pk_mul_f32 v[22:23], v[22:23], v[220:221]
	v_pk_mul_f32 v[24:25], v[24:25], v[222:223]
	v_pk_mul_f32 v[18:19], v[18:19], v[228:229]
	v_pk_mul_f32 v[20:21], v[20:21], v[230:231]
	v_pk_mul_f32 v[248:249], v[22:23], v[244:245] op_sel_hi:[1,0]
	v_pk_mul_f32 v[250:251], v[24:25], v[244:245] op_sel_hi:[1,0]
	v_pk_mul_f32 v[22:23], v[22:23], v[18:19]
	v_exp_f32_e32 v248, v248
	v_exp_f32_e32 v249, v249
	v_exp_f32_e32 v250, v250
	v_exp_f32_e32 v251, v251
	v_pk_mul_f32 v[24:25], v[24:25], v[20:21]
	v_pk_add_f32 v[248:249], v[248:249], 1.0 op_sel_hi:[1,0]
	v_pk_add_f32 v[250:251], v[250:251], 1.0 op_sel_hi:[1,0]
	v_rcp_f32_e32 v248, v248
	v_rcp_f32_e32 v249, v249
	v_rcp_f32_e32 v250, v250
	v_rcp_f32_e32 v251, v251
	v_pk_mul_f32 v[248:249], v[248:249], v[244:245] op_sel:[0,1] op_sel_hi:[1,1]
	v_pk_mul_f32 v[250:251], v[250:251], v[244:245] op_sel:[0,1] op_sel_hi:[1,1]
	v_pk_mul_f32 v[22:23], v[22:23], v[248:249]
	v_pk_mul_f32 v[24:25], v[24:25], v[250:251]
	v_cvt_pk_bf16_f32 v28, v22, v23
	v_cvt_pk_bf16_f32 v29, v24, v25
	s_add_u32 s22, s20, 0x5000
	s_addc_u32 s23, s21, 0
	global_store_dwordx4 v176, v[26:29], s[22:23] sc1
	v_pk_mul_f32 v[14:15], v[14:15], v[216:217]
	v_pk_mul_f32 v[16:17], v[16:17], v[218:219]
	v_pk_mul_f32 v[10:11], v[10:11], v[224:225]
	v_pk_mul_f32 v[12:13], v[12:13], v[226:227]
	v_pk_mul_f32 v[248:249], v[14:15], v[246:247] op_sel_hi:[1,0]
	v_pk_mul_f32 v[250:251], v[16:17], v[246:247] op_sel_hi:[1,0]
	v_pk_mul_f32 v[14:15], v[14:15], v[10:11]
	v_exp_f32_e32 v248, v248
	v_exp_f32_e32 v249, v249
	v_exp_f32_e32 v250, v250
	v_exp_f32_e32 v251, v251
	v_pk_mul_f32 v[16:17], v[16:17], v[12:13]
	v_pk_add_f32 v[248:249], v[248:249], 1.0 op_sel_hi:[1,0]
	v_pk_add_f32 v[250:251], v[250:251], 1.0 op_sel_hi:[1,0]
	v_rcp_f32_e32 v248, v248
	v_rcp_f32_e32 v249, v249
	v_rcp_f32_e32 v250, v250
	v_rcp_f32_e32 v251, v251
	v_pk_mul_f32 v[248:249], v[248:249], v[246:247] op_sel:[0,1] op_sel_hi:[1,1]
	v_pk_mul_f32 v[250:251], v[250:251], v[246:247] op_sel:[0,1] op_sel_hi:[1,1]
	v_pk_mul_f32 v[14:15], v[14:15], v[248:249]
	v_pk_mul_f32 v[16:17], v[16:17], v[250:251]
	v_cvt_pk_bf16_f32 v10, v14, v15
	v_cvt_pk_bf16_f32 v11, v16, v17
	v_pk_mul_f32 v[6:7], v[6:7], v[220:221]
	v_pk_mul_f32 v[8:9], v[8:9], v[222:223]
	v_pk_mul_f32 v[2:3], v[2:3], v[228:229]
	v_pk_mul_f32 v[4:5], v[4:5], v[230:231]
	v_pk_mul_f32 v[248:249], v[6:7], v[246:247] op_sel_hi:[1,0]
	v_pk_mul_f32 v[250:251], v[8:9], v[246:247] op_sel_hi:[1,0]
	v_pk_mul_f32 v[6:7], v[6:7], v[2:3]
	v_exp_f32_e32 v248, v248
	v_exp_f32_e32 v249, v249
	v_exp_f32_e32 v250, v250
	v_exp_f32_e32 v251, v251
	v_pk_mul_f32 v[8:9], v[8:9], v[4:5]
	v_pk_add_f32 v[248:249], v[248:249], 1.0 op_sel_hi:[1,0]
	v_pk_add_f32 v[250:251], v[250:251], 1.0 op_sel_hi:[1,0]
	v_rcp_f32_e32 v248, v248
	v_rcp_f32_e32 v249, v249
	v_rcp_f32_e32 v250, v250
	v_rcp_f32_e32 v251, v251
	v_pk_mul_f32 v[248:249], v[248:249], v[246:247] op_sel:[0,1] op_sel_hi:[1,1]
	v_pk_mul_f32 v[250:251], v[250:251], v[246:247] op_sel:[0,1] op_sel_hi:[1,1]
	v_pk_mul_f32 v[6:7], v[6:7], v[248:249]
	v_pk_mul_f32 v[8:9], v[8:9], v[250:251]
	v_cvt_pk_bf16_f32 v12, v6, v7
	v_cvt_pk_bf16_f32 v13, v8, v9
	global_store_dwordx4 v176, v[10:13], s[22:23] offset:2048 sc1
	s_mov_b64 s[20:21], -1
	s_andn2_b64 vcc, exec, s[4:5]
	s_cbranch_vccnz .LBB0_159
	s_andn2_b64 vcc, exec, s[6:7]
	s_cbranch_vccnz .LBB0_158
	s_barrier
	s_branch .LBB0_158

; #define PG8_STAGE(bufoff, gbase, voff) do { _Pragma("unroll") for (int _i = 0; _i < 2; ++_i) \
;         __builtin_amdgcn_global_load_lds((const unsigned*)((const char*)(gbase) + (voff)[_i]), (PG8_LAS unsigned*)(lds + (bufoff) + ldsw + _i * 8192), 16, 0, 0); } while (0)
; #define PG8_WAIT_V(n) asm volatile("s_waitcnt vmcnt(" #n ")" ::: "memory")
; #define PG8_BAR __builtin_amdgcn_s_barrier()
;     ...
;     if constexpr (SP2) {
;         PG8_STAGE(PG8_SB(0, 0), cB, voffB); PG8_STAGE(PG8_SB(0, 1), cB + hstepB, voffB); PG8_STAGE(PG8_SA(0, 0), cA, voffA); PG8_STAGE(PG8_SA(0, 1), cA + hstep, voffA);
;         if (wr == 1) PG8_BAR;
;         PG8_WAIT_V(2); PG8_BAR;
;         PG8_STAGE(PG8_SB(1, 0), cB + kstepB, voffB); PG8_STAGE(PG8_SA(1, 0), cA + kstep, voffA); PG8_STAGE(PG8_SB(1, 1), cB + hstepB + kstepB, voffB);
;         PG8_WAIT_V(6); PG8_BAR;
;     __device__ __forceinline__ void operator()(const i32x4 (&acc)[2][2][4][2], const pg8::Unit& u, int wr, int wc, int fr_, int fq_, int tid) {
;     ...
;         const float* cp = cmax + u.pn * 256 + wc * 32 + 8 * fq;
;         f32x4 cs[2][2];
;         cs[0][0] = *(const f32x4*)(cp) * (1.0f / 127.0f); cs[0][1] = *(const f32x4*)(cp + 4) * (1.0f / 127.0f);
;         cs[1][0] = *(const f32x4*)(cp + 128) * (1.0f / 127.0f); cs[1][1] = *(const f32x4*)(cp + 132) * (1.0f / 127.0f);
.LBB0_1133:
	s_add_u32 s8, s10, 0x2d800000
	s_addc_u32 s9, s11, 0
	s_mul_hi_i32 s14, s26, 0xb000
	s_mul_i32 s26, s26, 0xb000
	s_add_u32 s15, s10, s26
	s_addc_u32 s14, s11, s14
	s_lshl_b32 s10, s13, 5
	s_and_b32 s41, s10, 0x60
	s_lshl_b32 s40, s5, 6
	s_lshl_b32 s16, s5, 13
	s_lshl_b32 s13, s41, 7
	s_add_u32 s10, s22, 0x8000
	v_mov_b32_e32 v135, v163
	s_addc_u32 s11, s23, 0
	v_mov_b32_e32 v131, v163
	s_add_i32 m0, s36, 0x18000
	v_lshl_add_u64 v[12:13], s[10:11], 0, v[134:135]
	s_waitcnt vmcnt(2)
	s_barrier
	global_load_lds_dwordx4 v[12:13], off
	v_lshl_add_u64 v[12:13], s[10:11], 0, v[130:131]
	s_add_i32 m0, s36, 0x1a000
	s_add_i32 s42, s36, 0x8000
	s_add_i32 s43, s36, 0xa000
	global_load_lds_dwordx4 v[12:13], off
	v_lshl_add_u64 v[2:3], v[2:3], 0, s[78:79]
	s_mov_b32 m0, s42
	s_add_u32 s10, s22, 0xc000
	global_load_lds_dwordx4 v[2:3], off
	v_lshl_add_u64 v[2:3], v[4:5], 0, s[78:79]
	s_mov_b32 m0, s43
	s_addc_u32 s11, s23, 0
	global_load_lds_dwordx4 v[2:3], off
	s_add_i32 m0, s36, 0x1c000
	v_lshl_add_u64 v[2:3], s[10:11], 0, v[134:135]
	global_load_lds_dwordx4 v[2:3], off
	v_lshl_add_u64 v[2:3], s[10:11], 0, v[130:131]
	s_add_i32 m0, s36, 0x1e000
	v_bfe_u32 v155, v70, 4, 2
	global_load_lds_dwordx4 v[2:3], off
	v_and_b32_e32 v1, 15, v70
	v_lshlrev_b32_e32 v2, 4, v155
	v_lshlrev_b32_e32 v3, 2, v70
	v_lshl_or_b32 v2, v1, 6, v2
	v_and_b32_e32 v3, 32, v3
	v_bitop3_b32 v4, v2, s16, v3 bitop3:0xde
	v_bitop3_b32 v158, s13, v2, v3 bitop3:0xf6
	v_lshlrev_b32_e32 v2, 14, v10
	s_cmpk_lt_u32 s12, 0x100
	v_and_b32_e32 v2, 0xffff8000, v2
	s_sext_i32_i16 s21, s4
	s_cselect_b64 s[10:11], -1, 0
	s_ashr_i32 s44, s29, 31
	s_lshl_b32 s4, s41, 2
	v_lshl_add_u32 v2, v9, 11, v2
	v_and_b32_e32 v3, 1, v10
	s_add_u32 s4, s15, s4
	v_lshl_or_b32 v2, v3, 6, v2
	s_addc_u32 s12, s14, 0
	v_lshl_add_u32 v138, v11, 1, v2
	v_lshlrev_b32_e32 v2, 14, v6
	s_add_u32 s45, s4, 0x80000
	v_and_b32_e32 v2, 0xffff8000, v2
	s_waitcnt vmcnt(6)
	s_addc_u32 s46, s12, 0
	s_lshl_b32 s4, s5, 8
	v_lshl_add_u32 v2, v7, 11, v2
	v_and_b32_e32 v3, 1, v6
	s_add_i32 s47, s4, 0
	v_lshl_or_b32 v2, v3, 6, v2
	s_add_i32 s47, s47, 0x20400
	v_mov_b32_e32 v139, v163
	v_lshl_add_u32 v140, v8, 1, v2
	v_mov_b32_e32 v141, v163
	s_mov_b32 s48, 0
	v_add_u32_e32 v159, 0, v4
	v_and_b32_e32 v216, 31, v195
	v_lshrrev_b32_e32 v217, 5, v195
	v_lshl_add_u32 v216, v217, 7, v216
	v_lshlrev_b32_e32 v216, 2, v216
	s_lshl_b32 s96, s21, 10
	s_add_u32 s100, s45, s96
	s_addc_u32 s101, s46, 0
	global_load_dword v220, v216, s[100:101]
	s_add_u32 s100, s100, 0x1000
	s_addc_u32 s101, s101, 0
	global_load_dword v221, v216, s[100:101]
	s_add_u32 s100, s100, 0x1000
	s_addc_u32 s101, s101, 0
	global_load_dword v222, v216, s[100:101]
	s_add_u32 s100, s100, 0x1000
	s_addc_u32 s101, s101, 0
	global_load_dword v223, v216, s[100:101]
	s_add_u32 s100, s100, 0x1000
	s_addc_u32 s101, s101, 0
	global_load_dword v224, v216, s[100:101]
	s_add_u32 s100, s100, 0x1000
	s_addc_u32 s101, s101, 0
	global_load_dword v225, v216, s[100:101]
	s_add_u32 s100, s100, 0x1000
	s_addc_u32 s101, s101, 0
	global_load_dword v226, v216, s[100:101]
	s_add_u32 s100, s100, 0x1000
	s_addc_u32 s101, s101, 0
	global_load_dword v227, v216, s[100:101]
	s_add_u32 s100, s100, 0x1000
	s_addc_u32 s101, s101, 0
	global_load_dword v228, v216, s[100:101]
	s_add_u32 s100, s100, 0x1000
	s_addc_u32 s101, s101, 0
	global_load_dword v229, v216, s[100:101]
	s_add_u32 s100, s100, 0x1000
	s_addc_u32 s101, s101, 0
	global_load_dword v230, v216, s[100:101]
	s_lshl_b32 s96, s41, 3
	s_add_i32 s96, s96, 0x21000
	v_lshl_add_u32 v217, v195, 2, s96
	s_waitcnt vmcnt(0)
	v_mul_f32_e32 v220, s76, v220
	v_mul_f32_e32 v221, s76, v221
	v_mul_f32_e32 v222, s76, v222
	v_mul_f32_e32 v223, s76, v223
	v_mul_f32_e32 v224, s76, v224
	v_mul_f32_e32 v225, s76, v225
	v_mul_f32_e32 v226, s76, v226
	v_mul_f32_e32 v227, s76, v227
	v_mul_f32_e32 v228, s76, v228
	v_mul_f32_e32 v229, s76, v229
	v_mul_f32_e32 v230, s76, v230
	ds_write_b32 v217, v220
	ds_write_b32 v217, v221 offset:1024
	ds_write_b32 v217, v222 offset:2048
	ds_write_b32 v217, v223 offset:3072
	ds_write_b32 v217, v224 offset:4096
	ds_write_b32 v217, v225 offset:5120
	ds_write_b32 v217, v226 offset:6144
	ds_write_b32 v217, v227 offset:7168
	ds_write_b32 v217, v228 offset:8192
	ds_write_b32 v217, v229 offset:9216
	ds_write_b32 v217, v230 offset:10240
	s_waitcnt lgkmcnt(0)
	s_barrier
	s_branch .LBB0_1136

; #define LAS __attribute__((address_space(3)))
; template <unsigned PHMASK> __global__ void __launch_bounds__(NTHREADS, 2) fwd(Args a) {
;     extern __shared__ __attribute__((aligned(16))) unsigned char lds_raw[];
;     LAS unsigned char* lds = (LAS unsigned char*)lds_raw;
;     const int tid0 = threadIdx.x, G0 = gridDim.x, blk0 = blockIdx.x;
	.amdhsa_kernel _Z3fwdILj2047EEv4Args
		.amdhsa_group_segment_fixed_size 0
		.amdhsa_private_segment_fixed_size 0
		.amdhsa_kernarg_size 448
		.amdhsa_user_sgpr_count 2
		.amdhsa_user_sgpr_dispatch_ptr 0
		.amdhsa_user_sgpr_queue_ptr 0
		.amdhsa_user_sgpr_kernarg_segment_ptr 1
		.amdhsa_user_sgpr_dispatch_id 0
		.amdhsa_user_sgpr_kernarg_preload_length 0
		.amdhsa_user_sgpr_kernarg_preload_offset 0
		.amdhsa_user_sgpr_private_segment_size 0
		.amdhsa_uses_dynamic_stack 0
		.amdhsa_enable_private_segment 0
		.amdhsa_system_sgpr_workgroup_id_x 1
		.amdhsa_system_sgpr_workgroup_id_y 0
		.amdhsa_system_sgpr_workgroup_id_z 0
		.amdhsa_system_sgpr_workgroup_info 0
		.amdhsa_system_vgpr_workitem_id 0
		.amdhsa_next_free_vgpr 256
		.amdhsa_next_free_sgpr 102
		.amdhsa_accum_offset 256
		.amdhsa_reserve_vcc 1
		.amdhsa_float_round_mode_32 0
		.amdhsa_float_round_mode_16_64 0
		.amdhsa_float_denorm_mode_32 3
		.amdhsa_float_denorm_mode_16_64 3
		.amdhsa_dx10_clamp 1
		.amdhsa_ieee_mode 1
		.amdhsa_fp16_overflow 0
		.amdhsa_tg_split 0
		.amdhsa_exception_fp_ieee_invalid_op 0
		.amdhsa_exception_fp_denorm_src 0
		.amdhsa_exception_fp_ieee_div_zero 0
		.amdhsa_exception_fp_ieee_overflow 0
		.amdhsa_exception_fp_ieee_underflow 0
		.amdhsa_exception_fp_ieee_inexact 0
		.amdhsa_exception_int_div_zero 0
	.end_amdhsa_kernel

; #define LAS __attribute__((address_space(3)))
; template <unsigned PHMASK> __global__ void __launch_bounds__(NTHREADS, 2) fwd(Args a) {
;     extern __shared__ __attribute__((aligned(16))) unsigned char lds_raw[];
;     LAS unsigned char* lds = (LAS unsigned char*)lds_raw;
;     const int tid0 = threadIdx.x, G0 = gridDim.x, blk0 = blockIdx.x;
amdhsa.kernels:
  - .agpr_count:     0
    .args:
      - .offset:         0
        .size:           192
        .value_kind:     by_value
      - .offset:         192
        .size:           4
        .value_kind:     hidden_block_count_x
      - .offset:         196
        .size:           4
        .value_kind:     hidden_block_count_y
      - .offset:         200
        .size:           4
        .value_kind:     hidden_block_count_z
      - .offset:         204
        .size:           2
        .value_kind:     hidden_group_size_x
      - .offset:         206
        .size:           2
        .value_kind:     hidden_group_size_y
      - .offset:         208
        .size:           2
        .value_kind:     hidden_group_size_z
      - .offset:         210
        .size:           2
        .value_kind:     hidden_remainder_x
      - .offset:         212
        .size:           2
        .value_kind:     hidden_remainder_y
      - .offset:         214
        .size:           2
        .value_kind:     hidden_remainder_z
      - .offset:         232
        .size:           8
        .value_kind:     hidden_global_offset_x
      - .offset:         240
        .size:           8
        .value_kind:     hidden_global_offset_y
      - .offset:         248
        .size:           8
        .value_kind:     hidden_global_offset_z
      - .offset:         256
        .size:           2
        .value_kind:     hidden_grid_dims
      - .offset:         312
        .size:           4
        .value_kind:     hidden_dynamic_lds_size
    .group_segment_fixed_size: 0
    .kernarg_segment_align: 8
    .kernarg_segment_size: 448
    .language:       OpenCL C
    .language_version:
      - 2
      - 0
    .max_flat_workgroup_size: 512
    .name:           _Z3fwdILj2047EEv4Args
    .private_segment_fixed_size: 0
    .sgpr_count:     108
    .sgpr_spill_count: 104
    .symbol:         _Z3fwdILj2047EEv4Args.kd
    .uniform_work_group_size: 1
    .uses_dynamic_stack: false
    .vgpr_count:     256
    .vgpr_spill_count: 0
    .wavefront_size: 64
